# P2b next-layer weight conversion (w_in, w_uq, w_ukv) hand-batched: 3 rounds instead of 8 serial load-store rounds; alignment anchor after it
# baseline (speedup 1.0000x reference)
.LBB0_373:
	s_or_b64 exec, exec, s[30:31]
	v_readlane_b32 s0, v253, 0
	v_readlane_b32 s1, v253, 1
	s_add_i32 s0, s45, 1
	v_writelane_b32 v255, s0, 29
	s_cmp_lg_u32 s45, 3
	s_cselect_b64 s[4:5], -1, 0
	v_writelane_b32 v255, s1, 30
	v_readlane_b32 s0, v254, 11
	v_readlane_b32 s1, v254, 12
	v_writelane_b32 v255, s4, 31
	s_and_b64 s[0:1], s[0:1], s[4:5]
	v_mov_b32_e32 v26, v170
	v_readlane_b32 s2, v253, 2
	v_readlane_b32 s3, v253, 3
	v_writelane_b32 v255, s5, 32
	s_and_b64 vcc, exec, s[0:1]
	s_waitcnt lgkmcnt(0)
	s_barrier
	s_cbranch_vccz .LBB0_438
	s_mov_b64 s[20:21], exec
	v_readlane_b32 s0, v254, 13
	v_readlane_b32 s23, v255, 29
	v_readlane_b32 s4, v253, 20
	v_readlane_b32 s5, v253, 21
	v_readlane_b32 s6, v253, 30
	v_readlane_b32 s7, v253, 31
	v_readlane_b32 s8, v253, 28
	v_readlane_b32 s9, v253, 29
	s_nop 1
	v_add_u32_e32 v27, s0, v26
	s_mul_hi_u32 s1, s23, 0x1ba0000
	s_mul_i32 s0, s23, 0x1ba0000
	s_add_u32 s4, s4, s0
	s_addc_u32 s5, s5, s1
	s_mul_i32 s0, s23, 0xc0000
	s_add_u32 s6, s6, s0
	s_addc_u32 s7, s7, 0
	s_lshl_b32 s0, s23, 10
	s_add_u32 s8, s8, s0
	s_addc_u32 s9, s9, 0
	v_mov_b32_e32 v38, v27
	v_cmp_gt_u32_e32 vcc, 0x6d000, v38
	s_mov_b64 s[10:11], vcc
	s_mov_b32 s22, 0x12c9fc
	v_mul_hi_u32 v39, v38, s22
	v_mul_u32_u24_e32 v40, 0xda0, v39
	v_sub_u32_e32 v40, v38, v40
	v_mul_u32_u24_e32 v41, 0x37400, v39
	v_lshl_add_u32 v41, v40, 2, v41
	v_lshlrev_b32_e32 v24, 11, v40
	v_lshl_add_u32 v24, v39, 4, v24
	v_add_u32_e32 v24, 0x400000, v24
	s_mov_b64 exec, s[10:11]
	global_load_dword v0, v41, s[4:5]
	v_add_u32_e32 v41, 0x6e80, v41
	global_load_dword v1, v41, s[4:5]
	v_add_u32_e32 v41, 0x6e80, v41
	global_load_dword v2, v41, s[4:5]
	v_add_u32_e32 v41, 0x6e80, v41
	global_load_dword v3, v41, s[4:5]
	v_add_u32_e32 v41, 0x6e80, v41
	global_load_dword v4, v41, s[4:5]
	v_add_u32_e32 v41, 0x6e80, v41
	global_load_dword v5, v41, s[4:5]
	v_add_u32_e32 v41, 0x6e80, v41
	global_load_dword v6, v41, s[4:5]
	v_add_u32_e32 v41, 0x6e80, v41
	global_load_dword v7, v41, s[4:5]
	s_mov_b64 exec, s[20:21]
	s_mul_i32 s0, s76, 1
	v_add_u32_e32 v38, s0, v27
	v_cmp_gt_u32_e32 vcc, 0x6d000, v38
	s_mov_b64 s[12:13], vcc
	s_mov_b32 s22, 0x12c9fc
	v_mul_hi_u32 v39, v38, s22
	v_mul_u32_u24_e32 v40, 0xda0, v39
	v_sub_u32_e32 v40, v38, v40
	v_mul_u32_u24_e32 v41, 0x37400, v39
	v_lshl_add_u32 v41, v40, 2, v41
	v_lshlrev_b32_e32 v25, 11, v40
	v_lshl_add_u32 v25, v39, 4, v25
	v_add_u32_e32 v25, 0x400000, v25
	s_mov_b64 exec, s[12:13]
	global_load_dword v8, v41, s[4:5]
	v_add_u32_e32 v41, 0x6e80, v41
	global_load_dword v9, v41, s[4:5]
	v_add_u32_e32 v41, 0x6e80, v41
	global_load_dword v10, v41, s[4:5]
	v_add_u32_e32 v41, 0x6e80, v41
	global_load_dword v11, v41, s[4:5]
	v_add_u32_e32 v41, 0x6e80, v41
	global_load_dword v12, v41, s[4:5]
	v_add_u32_e32 v41, 0x6e80, v41
	global_load_dword v13, v41, s[4:5]
	v_add_u32_e32 v41, 0x6e80, v41
	global_load_dword v14, v41, s[4:5]
	v_add_u32_e32 v41, 0x6e80, v41
	global_load_dword v15, v41, s[4:5]
	s_mov_b64 exec, s[20:21]
	v_mov_b32_e32 v38, v27
	v_cmp_gt_u32_e32 vcc, 0x70000, v38
	s_mov_b64 s[14:15], vcc
	s_mov_b32 s22, 0x124925
	v_mul_hi_u32 v39, v38, s22
	v_mul_u32_u24_e32 v40, 0xe00, v39
	v_sub_u32_e32 v40, v38, v40
	v_mul_u32_u24_e32 v41, 0x37400, v39
	v_lshl_add_u32 v41, v40, 2, v41
	v_add_u32_e32 v41, 0x3680, v41
	v_lshlrev_b32_e32 v36, 11, v40
	v_lshl_add_u32 v36, v39, 4, v36
	v_add_u32_e32 v36, 0xb00000, v36
	s_mov_b64 exec, s[14:15]
	global_load_dword v16, v41, s[4:5]
	v_add_u32_e32 v41, 0x6e80, v41
	global_load_dword v17, v41, s[4:5]
	v_add_u32_e32 v41, 0x6e80, v41
	global_load_dword v18, v41, s[4:5]
	v_add_u32_e32 v41, 0x6e80, v41
	global_load_dword v19, v41, s[4:5]
	v_add_u32_e32 v41, 0x6e80, v41
	global_load_dword v20, v41, s[4:5]
	v_add_u32_e32 v41, 0x6e80, v41
	global_load_dword v21, v41, s[4:5]
	v_add_u32_e32 v41, 0x6e80, v41
	global_load_dword v22, v41, s[4:5]
	v_add_u32_e32 v41, 0x6e80, v41
	global_load_dword v23, v41, s[4:5]
	s_mov_b64 exec, s[20:21]
	s_mul_i32 s0, s76, 1
	v_add_u32_e32 v38, s0, v27
	v_cmp_gt_u32_e32 vcc, 0x70000, v38
	s_mov_b64 s[16:17], vcc
	s_mov_b32 s22, 0x124925
	v_mul_hi_u32 v39, v38, s22
	v_mul_u32_u24_e32 v40, 0xe00, v39
	v_sub_u32_e32 v40, v38, v40
	v_mul_u32_u24_e32 v41, 0x37400, v39
	v_lshl_add_u32 v41, v40, 2, v41
	v_add_u32_e32 v41, 0x3680, v41
	v_lshlrev_b32_e32 v37, 11, v40
	v_lshl_add_u32 v37, v39, 4, v37
	v_add_u32_e32 v37, 0xb00000, v37
	s_mov_b64 exec, s[16:17]
	global_load_dword v28, v41, s[4:5]
	v_add_u32_e32 v41, 0x6e80, v41
	global_load_dword v29, v41, s[4:5]
	v_add_u32_e32 v41, 0x6e80, v41
	global_load_dword v30, v41, s[4:5]
	v_add_u32_e32 v41, 0x6e80, v41
	global_load_dword v31, v41, s[4:5]
	v_add_u32_e32 v41, 0x6e80, v41
	global_load_dword v32, v41, s[4:5]
	v_add_u32_e32 v41, 0x6e80, v41
	global_load_dword v33, v41, s[4:5]
	v_add_u32_e32 v41, 0x6e80, v41
	global_load_dword v34, v41, s[4:5]
	v_add_u32_e32 v41, 0x6e80, v41
	global_load_dword v35, v41, s[4:5]
	s_mov_b64 exec, s[20:21]
	s_waitcnt vmcnt(0)
	s_mov_b64 exec, s[10:11]
	v_cvt_pk_bf16_f32 v0, v0, v1
	v_cvt_pk_bf16_f32 v1, v2, v3
	v_cvt_pk_bf16_f32 v2, v4, v5
	v_cvt_pk_bf16_f32 v3, v6, v7
	global_store_dwordx4 v24, v[0:3], s[2:3]
	s_mov_b64 exec, s[20:21]
	s_mov_b64 exec, s[12:13]
	v_cvt_pk_bf16_f32 v8, v8, v9
	v_cvt_pk_bf16_f32 v9, v10, v11
	v_cvt_pk_bf16_f32 v10, v12, v13
	v_cvt_pk_bf16_f32 v11, v14, v15
	global_store_dwordx4 v25, v[8:11], s[2:3]
	s_mov_b64 exec, s[20:21]
	s_mov_b64 exec, s[14:15]
	v_cvt_pk_bf16_f32 v16, v16, v17
	v_cvt_pk_bf16_f32 v17, v18, v19
	v_cvt_pk_bf16_f32 v18, v20, v21
	v_cvt_pk_bf16_f32 v19, v22, v23
	global_store_dwordx4 v36, v[16:19], s[2:3]
	s_mov_b64 exec, s[20:21]
	s_mov_b64 exec, s[16:17]
	v_cvt_pk_bf16_f32 v28, v28, v29
	v_cvt_pk_bf16_f32 v29, v30, v31
	v_cvt_pk_bf16_f32 v30, v32, v33
	v_cvt_pk_bf16_f32 v31, v34, v35
	global_store_dwordx4 v37, v[28:31], s[2:3]
	s_mov_b64 exec, s[20:21]
	s_mul_i32 s0, s76, 2
	v_add_u32_e32 v38, s0, v27
	v_cmp_gt_u32_e32 vcc, 0x6d000, v38
	s_mov_b64 s[10:11], vcc
	s_mov_b32 s22, 0x12c9fc
	v_mul_hi_u32 v39, v38, s22
	v_mul_u32_u24_e32 v40, 0xda0, v39
	v_sub_u32_e32 v40, v38, v40
	v_mul_u32_u24_e32 v41, 0x37400, v39
	v_lshl_add_u32 v41, v40, 2, v41
	v_lshlrev_b32_e32 v24, 11, v40
	v_lshl_add_u32 v24, v39, 4, v24
	v_add_u32_e32 v24, 0x400000, v24
	s_mov_b64 exec, s[10:11]
	global_load_dword v0, v41, s[4:5]
	v_add_u32_e32 v41, 0x6e80, v41
	global_load_dword v1, v41, s[4:5]
	v_add_u32_e32 v41, 0x6e80, v41
	global_load_dword v2, v41, s[4:5]
	v_add_u32_e32 v41, 0x6e80, v41
	global_load_dword v3, v41, s[4:5]
	v_add_u32_e32 v41, 0x6e80, v41
	global_load_dword v4, v41, s[4:5]
	v_add_u32_e32 v41, 0x6e80, v41
	global_load_dword v5, v41, s[4:5]
	v_add_u32_e32 v41, 0x6e80, v41
	global_load_dword v6, v41, s[4:5]
	v_add_u32_e32 v41, 0x6e80, v41
	global_load_dword v7, v41, s[4:5]
	s_mov_b64 exec, s[20:21]
	s_mul_i32 s0, s76, 3
	v_add_u32_e32 v38, s0, v27
	v_cmp_gt_u32_e32 vcc, 0x6d000, v38
	s_mov_b64 s[12:13], vcc
	s_mov_b32 s22, 0x12c9fc
	v_mul_hi_u32 v39, v38, s22
	v_mul_u32_u24_e32 v40, 0xda0, v39
	v_sub_u32_e32 v40, v38, v40
	v_mul_u32_u24_e32 v41, 0x37400, v39
	v_lshl_add_u32 v41, v40, 2, v41
	v_lshlrev_b32_e32 v25, 11, v40
	v_lshl_add_u32 v25, v39, 4, v25
	v_add_u32_e32 v25, 0x400000, v25
	s_mov_b64 exec, s[12:13]
	global_load_dword v8, v41, s[4:5]
	v_add_u32_e32 v41, 0x6e80, v41
	global_load_dword v9, v41, s[4:5]
	v_add_u32_e32 v41, 0x6e80, v41
	global_load_dword v10, v41, s[4:5]
	v_add_u32_e32 v41, 0x6e80, v41
	global_load_dword v11, v41, s[4:5]
	v_add_u32_e32 v41, 0x6e80, v41
	global_load_dword v12, v41, s[4:5]
	v_add_u32_e32 v41, 0x6e80, v41
	global_load_dword v13, v41, s[4:5]
	v_add_u32_e32 v41, 0x6e80, v41
	global_load_dword v14, v41, s[4:5]
	v_add_u32_e32 v41, 0x6e80, v41
	global_load_dword v15, v41, s[4:5]
	s_mov_b64 exec, s[20:21]
	s_mul_i32 s0, s76, 2
	v_add_u32_e32 v38, s0, v27
	v_cmp_gt_u32_e32 vcc, 0x70000, v38
	s_mov_b64 s[14:15], vcc
	s_mov_b32 s22, 0x124925
	v_mul_hi_u32 v39, v38, s22
	v_mul_u32_u24_e32 v40, 0xe00, v39
	v_sub_u32_e32 v40, v38, v40
	v_mul_u32_u24_e32 v41, 0x37400, v39
	v_lshl_add_u32 v41, v40, 2, v41
	v_add_u32_e32 v41, 0x3680, v41
	v_lshlrev_b32_e32 v36, 11, v40
	v_lshl_add_u32 v36, v39, 4, v36
	v_add_u32_e32 v36, 0xb00000, v36
	s_mov_b64 exec, s[14:15]
	global_load_dword v16, v41, s[4:5]
	v_add_u32_e32 v41, 0x6e80, v41
	global_load_dword v17, v41, s[4:5]
	v_add_u32_e32 v41, 0x6e80, v41
	global_load_dword v18, v41, s[4:5]
	v_add_u32_e32 v41, 0x6e80, v41
	global_load_dword v19, v41, s[4:5]
	v_add_u32_e32 v41, 0x6e80, v41
	global_load_dword v20, v41, s[4:5]
	v_add_u32_e32 v41, 0x6e80, v41
	global_load_dword v21, v41, s[4:5]
	v_add_u32_e32 v41, 0x6e80, v41
	global_load_dword v22, v41, s[4:5]
	v_add_u32_e32 v41, 0x6e80, v41
	global_load_dword v23, v41, s[4:5]
	s_mov_b64 exec, s[20:21]
	s_mul_i32 s0, s76, 3
	v_add_u32_e32 v38, s0, v27
	v_cmp_gt_u32_e32 vcc, 0x70000, v38
	s_mov_b64 s[16:17], vcc
	s_mov_b32 s22, 0x124925
	v_mul_hi_u32 v39, v38, s22
	v_mul_u32_u24_e32 v40, 0xe00, v39
	v_sub_u32_e32 v40, v38, v40
	v_mul_u32_u24_e32 v41, 0x37400, v39
	v_lshl_add_u32 v41, v40, 2, v41
	v_add_u32_e32 v41, 0x3680, v41
	v_lshlrev_b32_e32 v37, 11, v40
	v_lshl_add_u32 v37, v39, 4, v37
	v_add_u32_e32 v37, 0xb00000, v37
	s_mov_b64 exec, s[16:17]
	global_load_dword v28, v41, s[4:5]
	v_add_u32_e32 v41, 0x6e80, v41
	global_load_dword v29, v41, s[4:5]
	v_add_u32_e32 v41, 0x6e80, v41
	global_load_dword v30, v41, s[4:5]
	v_add_u32_e32 v41, 0x6e80, v41
	global_load_dword v31, v41, s[4:5]
	v_add_u32_e32 v41, 0x6e80, v41
	global_load_dword v32, v41, s[4:5]
	v_add_u32_e32 v41, 0x6e80, v41
	global_load_dword v33, v41, s[4:5]
	v_add_u32_e32 v41, 0x6e80, v41
	global_load_dword v34, v41, s[4:5]
	v_add_u32_e32 v41, 0x6e80, v41
	global_load_dword v35, v41, s[4:5]
	s_mov_b64 exec, s[20:21]
	s_waitcnt vmcnt(0)
	s_mov_b64 exec, s[10:11]
	v_cvt_pk_bf16_f32 v0, v0, v1
	v_cvt_pk_bf16_f32 v1, v2, v3
	v_cvt_pk_bf16_f32 v2, v4, v5
	v_cvt_pk_bf16_f32 v3, v6, v7
	global_store_dwordx4 v24, v[0:3], s[2:3]
	s_mov_b64 exec, s[20:21]
	s_mov_b64 exec, s[12:13]
	v_cvt_pk_bf16_f32 v8, v8, v9
	v_cvt_pk_bf16_f32 v9, v10, v11
	v_cvt_pk_bf16_f32 v10, v12, v13
	v_cvt_pk_bf16_f32 v11, v14, v15
	global_store_dwordx4 v25, v[8:11], s[2:3]
	s_mov_b64 exec, s[20:21]
	s_mov_b64 exec, s[14:15]
	v_cvt_pk_bf16_f32 v16, v16, v17
	v_cvt_pk_bf16_f32 v17, v18, v19
	v_cvt_pk_bf16_f32 v18, v20, v21
	v_cvt_pk_bf16_f32 v19, v22, v23
	global_store_dwordx4 v36, v[16:19], s[2:3]
	s_mov_b64 exec, s[20:21]
	s_mov_b64 exec, s[16:17]
	v_cvt_pk_bf16_f32 v28, v28, v29
	v_cvt_pk_bf16_f32 v29, v30, v31
	v_cvt_pk_bf16_f32 v30, v32, v33
	v_cvt_pk_bf16_f32 v31, v34, v35
	global_store_dwordx4 v37, v[28:31], s[2:3]
	s_mov_b64 exec, s[20:21]
	v_readlane_b32 s4, v253, 34
	v_readlane_b32 s5, v253, 35
	v_readlane_b32 s14, v253, 32
	v_readlane_b32 s15, v253, 33
	s_nop 1
	s_mul_i32 s0, s23, 0x80000
	s_add_u32 s4, s4, s0
	s_addc_u32 s5, s5, 0
	s_lshl_b32 s0, s23, 9
	s_add_u32 s14, s14, s0
	s_addc_u32 s15, s15, 0
	v_mov_b32_e32 v38, v27
	v_cmp_gt_u32_e32 vcc, 0x6000, v38
	s_mov_b64 s[10:11], vcc
	s_mov_b32 s22, 0x555556
	v_mul_hi_u32 v39, v38, s22
	v_mul_u32_u24_e32 v40, 0x300, v39
	v_sub_u32_e32 v40, v38, v40
	v_mul_u32_u24_e32 v41, 0x6000, v39
	v_lshl_add_u32 v41, v40, 2, v41
	v_lshlrev_b32_e32 v24, 9, v40
	v_lshl_add_u32 v24, v39, 4, v24
	v_add_u32_e32 v24, 0x1200000, v24
	v_lshlrev_b32_e32 v42, 5, v39
	s_mov_b64 exec, s[10:11]
	global_load_dword v0, v41, s[6:7]
	v_add_u32_e32 v41, 0xc00, v41
	global_load_dword v1, v41, s[6:7]
	v_add_u32_e32 v41, 0xc00, v41
	global_load_dword v2, v41, s[6:7]
	v_add_u32_e32 v41, 0xc00, v41
	global_load_dword v3, v41, s[6:7]
	v_add_u32_e32 v41, 0xc00, v41
	global_load_dword v4, v41, s[6:7]
	v_add_u32_e32 v41, 0xc00, v41
	global_load_dword v5, v41, s[6:7]
	v_add_u32_e32 v41, 0xc00, v41
	global_load_dword v6, v41, s[6:7]
	v_add_u32_e32 v41, 0xc00, v41
	global_load_dword v7, v41, s[6:7]
	global_load_dwordx4 v[8:11], v42, s[8:9]
	global_load_dwordx4 v[12:15], v42, s[8:9] offset:16
	s_mov_b64 exec, s[20:21]
	v_mov_b32_e32 v38, v27
	v_cmp_gt_u32_e32 vcc, 0x4000, v38
	s_mov_b64 s[12:13], vcc
	v_lshrrev_b32_e32 v39, 10, v38
	v_and_b32_e32 v40, 0x3ff, v38
	v_mul_u32_u24_e32 v41, 0x8000, v39
	v_lshl_add_u32 v41, v40, 2, v41
	v_lshlrev_b32_e32 v25, 8, v40
	v_lshl_add_u32 v25, v39, 4, v25
	v_add_u32_e32 v25, 0x1280000, v25
	v_lshlrev_b32_e32 v42, 5, v39
	s_mov_b64 exec, s[12:13]
	global_load_dword v16, v41, s[4:5]
	v_add_u32_e32 v41, 0x1000, v41
	global_load_dword v17, v41, s[4:5]
	v_add_u32_e32 v41, 0x1000, v41
	global_load_dword v18, v41, s[4:5]
	v_add_u32_e32 v41, 0x1000, v41
	global_load_dword v19, v41, s[4:5]
	v_add_u32_e32 v41, 0x1000, v41
	global_load_dword v20, v41, s[4:5]
	v_add_u32_e32 v41, 0x1000, v41
	global_load_dword v21, v41, s[4:5]
	v_add_u32_e32 v41, 0x1000, v41
	global_load_dword v22, v41, s[4:5]
	v_add_u32_e32 v41, 0x1000, v41
	global_load_dword v23, v41, s[4:5]
	global_load_dwordx4 v[28:31], v42, s[14:15]
	global_load_dwordx4 v[32:35], v42, s[14:15] offset:16
	s_mov_b64 exec, s[20:21]
	s_waitcnt vmcnt(0)
	s_mov_b64 exec, s[10:11]
	v_mul_f32_e32 v0, v0, v8
	v_mul_f32_e32 v1, v1, v9
	v_mul_f32_e32 v2, v2, v10
	v_mul_f32_e32 v3, v3, v11
	v_mul_f32_e32 v4, v4, v12
	v_mul_f32_e32 v5, v5, v13
	v_mul_f32_e32 v6, v6, v14
	v_mul_f32_e32 v7, v7, v15
	v_cvt_pk_bf16_f32 v0, v0, v1
	v_cvt_pk_bf16_f32 v1, v2, v3
	v_cvt_pk_bf16_f32 v2, v4, v5
	v_cvt_pk_bf16_f32 v3, v6, v7
	global_store_dwordx4 v24, v[0:3], s[2:3]
	s_mov_b64 exec, s[20:21]
	s_mov_b64 exec, s[12:13]
	v_mul_f32_e32 v16, v16, v28
	v_mul_f32_e32 v17, v17, v29
	v_mul_f32_e32 v18, v18, v30
	v_mul_f32_e32 v19, v19, v31
	v_mul_f32_e32 v20, v20, v32
	v_mul_f32_e32 v21, v21, v33
	v_mul_f32_e32 v22, v22, v34
	v_mul_f32_e32 v23, v23, v35
	v_cvt_pk_bf16_f32 v16, v16, v17
	v_cvt_pk_bf16_f32 v17, v18, v19
	v_cvt_pk_bf16_f32 v18, v20, v21
	v_cvt_pk_bf16_f32 v19, v22, v23
	global_store_dwordx4 v25, v[16:19], s[2:3]
	s_mov_b64 exec, s[20:21]
	v_cmp_gt_u32_e32 vcc, 0x3000, v27
	v_lshlrev_b32_e32 v38, 4, v27
	v_add_u32_e32 v38, 0xad0000, v38
	v_mov_b32_e32 v0, 0
	v_mov_b32_e32 v1, 0
	v_mov_b32_e32 v2, 0
	v_mov_b32_e32 v3, 0
	s_and_b64 exec, s[20:21], vcc
	global_store_dwordx4 v38, v[0:3], s[2:3]
	s_mov_b64 exec, s[20:21]
	.p2align 6
	s_nop 0
	s_nop 0
	s_nop 0
	s_nop 0
	s_nop 0
	s_nop 0
